# attention: s_setprio 1 for waves 4-7 during S1 only, on top of hand-scheduled S2
# speedup vs baseline: 1.0180x; 1.0124x over previous
; #define MFMA32(a, b, c) __builtin_amdgcn_mfma_f32_32x32x16_bf16((a), (b), (c), 0, 0, 0)
; #define LOADV(dst, ks_) do { _Pragma("unroll") for (int dvb = 0; dvb < 4; ++dvb) { dst[2 * dvb] = vtr(vp + dvb * 4096 + (ks_) * 1024); dst[2 * dvb + 1] = vtr(vp + dvb * 4096 + (ks_) * 1024 + 512); } } while (0)
; DI void attn_unit(const Params& p, int bh, int qb, char* lds, float lam, int tid, int lane, int wid, const bool build_tab) {
;     ...
;         if (act) {
;             const lds_cptr kp = (lds_cptr)lds + sc + map * 8192 + hi * 1024 + r32 * 16;
;             bf16x8 kf[8];
; #pragma unroll
;             for (int d0 = 0; d0 < 4; ++d0) {
;                 kf[2 * d0] = *(const __attribute__((address_space(3))) bf16x8*)(kp + d0 * 2048);
;                 kf[2 * d0 + 1] = *(const __attribute__((address_space(3))) bf16x8*)(kp + d0 * 2048 + 512);
;             }
;             f32x16 s0 = cinit, s1 = cinit;
; #pragma unroll
;             for (int d0 = 0; d0 < 4; ++d0) { s0 = MFMA32(kf[2 * d0], qf[d0], s0); s1 = MFMA32(kf[2 * d0 + 1], qf[d0], s1); }
;             LOADV(va, 0);
;             if (t >= 2 * qb - 2) {
;                 const float* tb = tab + (64 * t - (qrow0 + r32) + 256 + 4 * hi);
; #pragma unroll
;                 for (int i = 0; i < 16; ++i) {
;                     s0[i] += tb[(i & 3) + 8 * (i >> 2)];
;                     s1[i] += tb[(i & 3) + 8 * (i >> 2) + 32];
;                 }
;             }
.LBB0_352:
	s_andn2_b64 vcc, exec, s[50:51]
	s_cbranch_vccnz .LBB0_360
	s_cmp_lt_u32 s59, 64
	s_cbranch_scc1 .Lp3_1
	s_setprio 1
.Lp3_1:
	s_add_i32 s50, s84, 0
	s_add_i32 s51, s50, s61
	v_add3_u32 v136, s51, v204, v205
	ds_read_b128 v[80:83], v136
	ds_read_b128 v[128:131], v136 offset:512
	s_cmp_lt_u32 s7, s79
	s_waitcnt lgkmcnt(1)
	v_mfma_f32_32x32x16_bf16 v[96:111], v[80:83], v[112:115], v[64:79]
	s_waitcnt lgkmcnt(0)
	v_mfma_f32_32x32x16_bf16 v[80:95], v[128:131], v[112:115], v[64:79]
	ds_read_b128 v[128:131], v136 offset:2048
	ds_read_b128 v[132:135], v136 offset:2560
	s_waitcnt lgkmcnt(1)
	v_mfma_f32_32x32x16_bf16 v[96:111], v[128:131], v[116:119], v[96:111]
	s_waitcnt lgkmcnt(0)
	v_mfma_f32_32x32x16_bf16 v[80:95], v[132:135], v[116:119], v[80:95]
	ds_read_b128 v[128:131], v136 offset:4096
	ds_read_b128 v[132:135], v136 offset:4608
	ds_read_b128 v[222:225], v136 offset:6656
	s_waitcnt lgkmcnt(2)
	v_mfma_f32_32x32x16_bf16 v[96:111], v[128:131], v[120:123], v[96:111]
	ds_read_b128 v[128:131], v136 offset:6144
	s_waitcnt lgkmcnt(2)
	v_mfma_f32_32x32x16_bf16 v[80:95], v[132:135], v[120:123], v[80:95]
	v_add3_u32 v132, s50, v171, v202
	v_add_u32_e32 v220, v132, v203
	s_waitcnt lgkmcnt(0)
	v_mfma_f32_32x32x16_bf16 v[96:111], v[128:131], v[124:127], v[96:111]
	ds_read_b64_tr_b16 v[140:141], v220 offset:16384
	ds_read_b64_tr_b16 v[142:143], v220 offset:16896
	ds_read_b64_tr_b16 v[136:137], v220 offset:20480
	ds_read_b64_tr_b16 v[138:139], v220 offset:20992
	ds_read_b64_tr_b16 v[132:133], v220 offset:24576
	ds_read_b64_tr_b16 v[134:135], v220 offset:25088
	ds_read_b64_tr_b16 v[128:129], v220 offset:28672
	ds_read_b64_tr_b16 v[130:131], v220 offset:29184
	v_mfma_f32_32x32x16_bf16 v[80:95], v[222:225], v[124:127], v[80:95]
	s_cbranch_scc1 .LBB0_355
	v_add_u32_e32 v221, s83, v219
	v_add_u32_e32 v222, 0x18600, v221
	v_add_u32_e32 v224, 0x18680, v221
	v_add_u32_e32 v226, 0x18608, v221
	v_add_u32_e32 v228, 0x18688, v221
	v_add_u32_e32 v230, 0x18620, v221
	v_add_u32_e32 v232, 0x186a0, v221
	v_add_u32_e32 v234, 0x18628, v221
	v_add_u32_e32 v236, 0x186a8, v221
	v_add_u32_e32 v238, 0x18640, v221
	v_add_u32_e32 v240, 0x186c0, v221
	v_add_u32_e32 v242, 0x18648, v221
	v_add_u32_e32 v244, 0x186c8, v221
	v_add_u32_e32 v248, 0x18660, v221
	v_add_u32_e32 v250, 0x186e0, v221
	v_add_u32_e32 v246, 0x18668, v221
	ds_read2_b32 v[222:223], v222 offset1:1
	ds_read2_b32 v[224:225], v224 offset1:1
	ds_read2_b32 v[226:227], v226 offset1:1
	ds_read2_b32 v[228:229], v228 offset1:1
	ds_read2_b32 v[230:231], v230 offset1:1
	ds_read2_b32 v[232:233], v232 offset1:1
	ds_read2_b32 v[234:235], v234 offset1:1
	ds_read2_b32 v[236:237], v236 offset1:1
	ds_read2_b32 v[238:239], v238 offset1:1
	ds_read2_b32 v[240:241], v240 offset1:1
	ds_read2_b32 v[242:243], v242 offset1:1
	ds_read2_b32 v[244:245], v244 offset1:1
	ds_read2_b32 v[246:247], v246 offset1:1
	ds_read2_b32 v[248:249], v248 offset1:1
	v_add_u32_e32 v221, 0x186e8, v221
	ds_read2_b32 v[250:251], v250 offset1:1
	ds_read2_b32 v[252:253], v221 offset1:1
	s_waitcnt lgkmcnt(5)
	v_pk_add_f32 v[106:107], v[106:107], v[242:243]
	s_waitcnt lgkmcnt(3)
	v_pk_add_f32 v[110:111], v[110:111], v[246:247]
	s_waitcnt lgkmcnt(2)
	v_pk_add_f32 v[108:109], v[108:109], v[248:249]
	v_pk_add_f32 v[104:105], v[104:105], v[238:239]
	v_pk_add_f32 v[102:103], v[102:103], v[234:235]
	v_pk_add_f32 v[100:101], v[100:101], v[230:231]
	v_pk_add_f32 v[98:99], v[98:99], v[226:227]
	v_pk_add_f32 v[96:97], v[96:97], v[222:223]
	s_waitcnt lgkmcnt(0)
	v_pk_add_f32 v[94:95], v[94:95], v[252:253]
	v_pk_add_f32 v[92:93], v[92:93], v[250:251]
	v_pk_add_f32 v[90:91], v[90:91], v[244:245]
	v_pk_add_f32 v[88:89], v[88:89], v[240:241]
	v_pk_add_f32 v[86:87], v[86:87], v[236:237]
	v_pk_add_f32 v[84:85], v[84:85], v[232:233]
	v_pk_add_f32 v[82:83], v[82:83], v[228:229]
	v_pk_add_f32 v[80:81], v[80:81], v[224:225]

; #define GLOAD(t_, slotoff_) do { const char* kb_ = KGc + ((size_t)(t_) << 14); const char* vb_ = VGc + ((size_t)(t_) << 14); \
;         const unsigned d_ = (unsigned)__builtin_amdgcn_readfirstlane((int)(ldsbase + (slotoff_) + wid * 1024)); \
;         GLDS16(kb_, d_); GLDS16(kb_ + 8192, d_ + 8192u); GLDS16(vb_, d_ + 16384u); GLDS16(vb_ + 8192, d_ + 24576u); } while (0)
; DI void attn_unit(const Params& p, int bh, int qb, char* lds, float lam, int tid, int lane, int wid, const bool build_tab) {
;     ...
;             asm volatile("s_waitcnt vmcnt(0)" ::: "memory");
;             if (t + 2 < NT) GLOAD(t + 2, sn2);
.LBB0_357:
	s_setprio 0
	s_waitcnt vmcnt(0)
	s_cmp_ge_u32 s7, s77
	s_cbranch_scc1 .LBB0_359
	s_add_i32 s92, s82, s93
	s_mov_b32 m0, s92
	s_nop 0
	global_load_lds_dwordx4 v[200:201], off
	global_load_lds_dwordx4 v[200:201], off offset:1024
	global_load_lds_dwordx4 v[200:201], off offset:2048
	global_load_lds_dwordx4 v[200:201], off offset:3072

; #define MFMA32(a, b, c) __builtin_amdgcn_mfma_f32_32x32x16_bf16((a), (b), (c), 0, 0, 0)
; #define LOADV(dst, ks_) do { _Pragma("unroll") for (int dvb = 0; dvb < 4; ++dvb) { dst[2 * dvb] = vtr(vp + dvb * 4096 + (ks_) * 1024); dst[2 * dvb + 1] = vtr(vp + dvb * 4096 + (ks_) * 1024 + 512); } } while (0)
; DI void attn_unit(const Params& p, int bh, int qb, char* lds, float lam, int tid, int lane, int wid, const bool build_tab) {
;     ...
;         if (act) {
;             const lds_cptr kp = (lds_cptr)lds + sc + map * 8192 + hi * 1024 + r32 * 16;
;             bf16x8 kf[8];
; #pragma unroll
;             for (int d0 = 0; d0 < 4; ++d0) {
;                 kf[2 * d0] = *(const __attribute__((address_space(3))) bf16x8*)(kp + d0 * 2048);
;                 kf[2 * d0 + 1] = *(const __attribute__((address_space(3))) bf16x8*)(kp + d0 * 2048 + 512);
;             }
;             f32x16 s0 = cinit, s1 = cinit;
; #pragma unroll
;             for (int d0 = 0; d0 < 4; ++d0) { s0 = MFMA32(kf[2 * d0], qf[d0], s0); s1 = MFMA32(kf[2 * d0 + 1], qf[d0], s1); }
;             LOADV(va, 0);
;             if (t >= 2 * qb - 2) {
;                 const float* tb = tab + (64 * t - (qrow0 + r32) + 256 + 4 * hi);
; #pragma unroll
;                 for (int i = 0; i < 16; ++i) {
;                     s0[i] += tb[(i & 3) + 8 * (i >> 2)];
;                     s1[i] += tb[(i & 3) + 8 * (i >> 2) + 32];
;                 }
;             }
.LBB0_372:
	s_andn2_b64 vcc, exec, s[52:53]
	s_cbranch_vccnz .LBB0_380
	s_cmp_lt_u32 s59, 64
	s_cbranch_scc1 .Lp3_0
	s_setprio 1
.Lp3_0:
	s_add_i32 s52, s70, 0
	s_add_i32 s53, s52, s61
	v_add3_u32 v136, s53, v204, v205
	ds_read_b128 v[80:83], v136
	ds_read_b128 v[128:131], v136 offset:512
	s_cmp_lt_i32 s51, s57
	s_waitcnt lgkmcnt(1)
	v_mfma_f32_32x32x16_bf16 v[96:111], v[80:83], v[112:115], v[64:79]
	s_waitcnt lgkmcnt(0)
	v_mfma_f32_32x32x16_bf16 v[80:95], v[128:131], v[112:115], v[64:79]
	ds_read_b128 v[128:131], v136 offset:2048
	ds_read_b128 v[132:135], v136 offset:2560
	s_waitcnt lgkmcnt(1)
	v_mfma_f32_32x32x16_bf16 v[96:111], v[128:131], v[116:119], v[96:111]
	s_waitcnt lgkmcnt(0)
	v_mfma_f32_32x32x16_bf16 v[80:95], v[132:135], v[116:119], v[80:95]
	ds_read_b128 v[128:131], v136 offset:4096
	ds_read_b128 v[132:135], v136 offset:4608
	ds_read_b128 v[178:181], v136 offset:6656
	s_waitcnt lgkmcnt(2)
	v_mfma_f32_32x32x16_bf16 v[96:111], v[128:131], v[120:123], v[96:111]
	ds_read_b128 v[128:131], v136 offset:6144
	s_waitcnt lgkmcnt(2)
	v_mfma_f32_32x32x16_bf16 v[80:95], v[132:135], v[120:123], v[80:95]
	v_add3_u32 v132, s52, v171, v202
	v_add_u32_e32 v177, v132, v203
	s_waitcnt lgkmcnt(0)
	v_mfma_f32_32x32x16_bf16 v[96:111], v[128:131], v[124:127], v[96:111]
	ds_read_b64_tr_b16 v[140:141], v177 offset:16384
	ds_read_b64_tr_b16 v[142:143], v177 offset:16896
	ds_read_b64_tr_b16 v[136:137], v177 offset:20480
	ds_read_b64_tr_b16 v[138:139], v177 offset:20992
	ds_read_b64_tr_b16 v[132:133], v177 offset:24576
	ds_read_b64_tr_b16 v[134:135], v177 offset:25088
	ds_read_b64_tr_b16 v[128:129], v177 offset:28672
	ds_read_b64_tr_b16 v[130:131], v177 offset:29184
	v_mfma_f32_32x32x16_bf16 v[80:95], v[178:181], v[124:127], v[80:95]
	s_cbranch_scc1 .LBB0_375
	v_add_u32_e32 v219, s69, v146
	v_add_u32_e32 v178, 0x18600, v219
	v_add_u32_e32 v180, 0x18680, v219
	v_add_u32_e32 v182, 0x18608, v219
	v_add_u32_e32 v184, 0x18688, v219
	v_add_u32_e32 v186, 0x18620, v219
	v_add_u32_e32 v188, 0x186a0, v219
	v_add_u32_e32 v190, 0x18628, v219
	v_add_u32_e32 v192, 0x186a8, v219
	v_add_u32_e32 v194, 0x18640, v219
	v_add_u32_e32 v196, 0x186c0, v219
	v_add_u32_e32 v198, 0x18648, v219
	v_add_u32_e32 v220, 0x186c8, v219
	v_add_u32_e32 v224, 0x18660, v219
	v_add_u32_e32 v226, 0x186e0, v219
	v_add_u32_e32 v222, 0x18668, v219
	ds_read2_b32 v[178:179], v178 offset1:1
	ds_read2_b32 v[180:181], v180 offset1:1
	ds_read2_b32 v[182:183], v182 offset1:1
	ds_read2_b32 v[184:185], v184 offset1:1
	ds_read2_b32 v[186:187], v186 offset1:1
	ds_read2_b32 v[188:189], v188 offset1:1
	ds_read2_b32 v[190:191], v190 offset1:1
	ds_read2_b32 v[192:193], v192 offset1:1
	ds_read2_b32 v[194:195], v194 offset1:1
	ds_read2_b32 v[196:197], v196 offset1:1
	ds_read2_b32 v[198:199], v198 offset1:1
	ds_read2_b32 v[220:221], v220 offset1:1
	ds_read2_b32 v[222:223], v222 offset1:1
	ds_read2_b32 v[224:225], v224 offset1:1
	v_add_u32_e32 v219, 0x186e8, v219
	ds_read2_b32 v[226:227], v226 offset1:1
	ds_read2_b32 v[228:229], v219 offset1:1
	s_waitcnt lgkmcnt(5)
	v_pk_add_f32 v[106:107], v[106:107], v[198:199]
	s_waitcnt lgkmcnt(3)
	v_pk_add_f32 v[110:111], v[110:111], v[222:223]
	s_waitcnt lgkmcnt(2)
	v_pk_add_f32 v[108:109], v[108:109], v[224:225]
	v_pk_add_f32 v[104:105], v[104:105], v[194:195]
	v_pk_add_f32 v[102:103], v[102:103], v[190:191]
	v_pk_add_f32 v[100:101], v[100:101], v[186:187]
	v_pk_add_f32 v[98:99], v[98:99], v[182:183]
	v_pk_add_f32 v[96:97], v[96:97], v[178:179]
	s_waitcnt lgkmcnt(0)
	v_pk_add_f32 v[94:95], v[94:95], v[228:229]
	v_pk_add_f32 v[92:93], v[92:93], v[226:227]
	v_pk_add_f32 v[90:91], v[90:91], v[220:221]
	v_pk_add_f32 v[88:89], v[88:89], v[196:197]
	v_pk_add_f32 v[86:87], v[86:87], v[192:193]
	v_pk_add_f32 v[84:85], v[84:85], v[188:189]
	v_pk_add_f32 v[82:83], v[82:83], v[184:185]
	v_pk_add_f32 v[80:81], v[80:81], v[180:181]

; #define GLOAD(t_, slotoff_) do { const char* kb_ = KGc + ((size_t)(t_) << 14); const char* vb_ = VGc + ((size_t)(t_) << 14); \
;         const unsigned d_ = (unsigned)__builtin_amdgcn_readfirstlane((int)(ldsbase + (slotoff_) + wid * 1024)); \
;         GLDS16(kb_, d_); GLDS16(kb_ + 8192, d_ + 8192u); GLDS16(vb_, d_ + 16384u); GLDS16(vb_ + 8192, d_ + 24576u); } while (0)
; DI void attn_unit(const Params& p, int bh, int qb, char* lds, float lam, int tid, int lane, int wid, const bool build_tab) {
;     ...
;             asm volatile("s_waitcnt vmcnt(0)" ::: "memory");
;             if (t + 2 < NT) GLOAD(t + 2, sn2);
.LBB0_377:
	s_setprio 0
	s_waitcnt vmcnt(0)
	s_cmp_ge_u32 s51, s55
	s_cbranch_scc1 .LBB0_379
	s_add_i32 s92, s67, s93
	s_mov_b32 m0, s92
	s_nop 0
	global_load_lds_dwordx4 v[174:175], off
	global_load_lds_dwordx4 v[174:175], off offset:1024
	global_load_lds_dwordx4 v[174:175], off offset:2048
	global_load_lds_dwordx4 v[174:175], off offset:3072
